# v25 with the whole instruction stream shifted by 4 bytes (one s_nop at entry): code-placement check
# speedup vs baseline: 1.0016x; 1.0016x over previous
; #define LAS __attribute__((address_space(3)))
; #define PG8_LAS __attribute__((address_space(3)))
; __device__ __forceinline__ unsigned xb_ld(unsigned* p)              { return __hip_atomic_load(p, __ATOMIC_RELAXED, __HIP_MEMORY_SCOPE_AGENT); }
; __device__ __forceinline__ unsigned xb_add(unsigned* p, unsigned v) { return __hip_atomic_fetch_add(p, v, __ATOMIC_RELAXED, __HIP_MEMORY_SCOPE_AGENT); }
; __device__ __forceinline__ unsigned xb_xcc_id() { return (unsigned)__builtin_amdgcn_s_getreg((3 << 11) | 20) & 0xFu; }
; __device__ __forceinline__ XcdBarrier xcd_barrier_post(unsigned* bar, volatile LAS unsigned* st) {
;     XcdBarrier b; b.bar = bar; b.x = xb_xcc_id(); b.st = st;
;     if (threadIdx.x == 0) (void)xb_add(&bar[XB_XCNT(b.x)], 1u);
;     return b;
; }
; __global__ void __launch_bounds__(512, 2) mega_fwd(Args a) {
;   extern __shared__ __attribute__((aligned(16))) unsigned char lds[];
;   cg::grid_group grid = cg::this_grid();
;   const int tid = threadIdx.x, lane = tid & 63, wave = __builtin_amdgcn_readfirstlane(tid >> 6);
;   const int G = gridDim.x, bx = blockIdx.x;
;   const int gw = bx * 8 + wave, NGW = G * 8;
;   unsigned char* ws = a.ws; float* out = a.out;
;   const float* x_p = a.in[0]; const float* x_s = a.in[1];
;   bf16_t* WT_IN = (bf16_t*)(ws + WS_WT_IN); bf16_t* WT_MRG = (bf16_t*)(ws + WS_WT_MRG); bf16_t* WT_OUT = (bf16_t*)(ws + WS_WT_OUT);
;   bf16_t* WT_UP = (bf16_t*)(ws + WS_WT_UP); bf16_t* WT_DN = (bf16_t*)(ws + WS_WT_DN); bf16_t* XN = (bf16_t*)(ws + WS_XN);
;   bf16_t* QKV = (bf16_t*)(ws + WS_QKV); bf16_t* GATES = (bf16_t*)(ws + WS_GATES); float* LOGF = (float*)(ws + WS_LOGF);
;   bf16_t* ATT = (bf16_t*)(ws + WS_ATT); bf16_t* T1 = (bf16_t*)(ws + WS_T1); bf16_t* GB = (bf16_t*)(ws + WS_G); bf16_t* MO = (bf16_t*)(ws + WS_MO);
;   bf16_t* HH = (bf16_t*)(ws + WS_HH); float* TAIL = (float*)(ws + WS_TAIL); float* HEAD = (float*)(ws + WS_HEAD); float* PART = (float*)(ws + WS_ATT); float* NRM = (float*)(ws + WS_LOGF + 768 * 1024);
;   PG8_LAS unsigned char* ldsl = (PG8_LAS unsigned char*)lds;
;   const int lo = a.ph_lo, hi = a.ph_hi;
;   volatile LAS unsigned* MISC = (volatile LAS unsigned*)((LAS unsigned char*)lds + MISC_OFF);
;   if (tid < 32) MISC[tid] = 0u;
;   __syncthreads();
;   const XcdBarrier bar = xcd_barrier_post((unsigned*)(ws + WS_BAR), MISC + 8);
_Z8mega_fwd4Args:
	s_nop 0
	s_load_dword s3, s[0:1], 0xf8
	s_load_dwordx8 s[88:95], s[0:1], 0xc0
	s_load_dwordx4 s[84:87], s[0:1], 0xe0
	s_load_dwordx2 s[82:83], s[0:1], 0xf0
	s_mov_b32 s68, s2
	s_add_u32 s2, s0, 0xf0
	v_and_b32_e32 v1, 0x3ff, v0
	s_waitcnt lgkmcnt(0)
	v_writelane_b32 v251, s3, 0
	s_addc_u32 s3, s1, 0
	v_writelane_b32 v251, s2, 1
	v_readfirstlane_b32 s6, v1
	v_cmp_gt_u32_e32 vcc, 32, v1
	v_writelane_b32 v251, s3, 2
	s_and_saveexec_b64 s[2:3], vcc
	v_lshl_add_u32 v2, v1, 2, 0
	v_add_u32_e32 v2, 0x25f80, v2
	v_mov_b32_e32 v3, 0
	ds_write_b32 v2, v3
	s_or_b64 exec, exec, s[2:3]
	s_load_dwordx16 s[8:23], s[0:1], 0x0
	s_waitcnt lgkmcnt(0)
	s_barrier
	s_add_u32 s56, s84, 0x225c8000
	v_writelane_b32 v251, s8, 3
	s_getreg_b32 s2, hwreg(HW_REG_XCC_ID, 0, 4)
	s_addc_u32 s57, s85, 0
	v_writelane_b32 v251, s9, 4
	v_writelane_b32 v251, s10, 5
	v_writelane_b32 v251, s11, 6
	v_writelane_b32 v251, s12, 7
	v_writelane_b32 v251, s13, 8
	v_writelane_b32 v251, s14, 9
	v_writelane_b32 v251, s15, 10
	v_writelane_b32 v251, s16, 11
	v_writelane_b32 v251, s17, 12
	v_writelane_b32 v251, s18, 13
	v_writelane_b32 v251, s19, 14
	v_writelane_b32 v251, s20, 15
	v_writelane_b32 v251, s21, 16
	v_writelane_b32 v251, s22, 17
	s_and_b32 s79, s2, 15
	v_writelane_b32 v251, s23, 18
	v_cmp_eq_u32_e64 s[4:5], 0, v1
	s_mov_b64 s[2:3], exec
	s_nop 0
	v_writelane_b32 v251, s4, 19
	s_nop 1
	v_writelane_b32 v251, s5, 20
	s_and_b64 s[4:5], s[2:3], s[4:5]
	s_mov_b64 exec, s[4:5]
	s_cbranch_execz .LBB0_5
	s_mov_b64 s[4:5], exec
	v_mbcnt_lo_u32_b32 v2, s4, 0
	v_mbcnt_hi_u32_b32 v2, s5, v2
	v_cmp_eq_u32_e32 vcc, 0, v2
	s_and_b64 s[8:9], exec, vcc
	s_mov_b64 exec, s[8:9]
	s_cbranch_execz .LBB0_5
	s_lshl_b32 s7, s79, 8
	s_bcnt1_i32_b64 s4, s[4:5]
	v_mov_b32_e32 v2, s7
	v_mov_b32_e32 v3, s4
	global_atomic_add v2, v3, s[56:57] offset:1024
